# adds: GLA pass C backward chunk step touches the output-gate rows at the step top and issues gate/gain loads at finalize start (latency hidden under the row reduction)
# speedup vs baseline: 1.0047x; 1.0047x over previous
; __device__ __forceinline__ int crow(int r, int hi) { return (r & 3) + 8 * (r >> 2) + 4 * hi; }
; __device__ __forceinline__ void passC(const Params& p, const bf16* Hb, const float* SEG, float* Z0, bf16* MIX, LAS unsigned char* lds, int bid, int G, int wave_u) {
;     ...
;                 const int rowbase = (sg * SEGC + (dir ? SEGC - 1 - n : n)) * 64;
;                 const ChunkRegs C = R; const int cur = n & 1; const int LV = cur ? L_V2 : L_V;
;                 if (n + 1 < SEGC) chunk_load<true>(R, Hb, (sg * SEGC + (dir ? SEGC - 2 - n : n + 1)) * 64, head, dir, tid);
;                 f32x16 Z;
;                 float* Zg = Z0 + (size_t)(rowbase + 32 * pb) * 512 + head * 128 + 32 * db + r32;
;                 if (dir == 0) {
; #pragma unroll
;                     for (int r = 0; r < 16; ++r) Z[r] = 0.f;
;                 } else {
; #pragma unroll
;                     for (int r = 0; r < 16; ++r) Z[r] = Zg[(size_t)crow(r, hh) * 512];
.LBB0_522:
	s_add_i32 s48, s53, -1
	s_and_b64 s[44:45], s[60:61], exec
	s_cselect_b32 s44, s48, s49
	s_or_b32 s44, s44, s51
	s_lshl_b32 s65, s44, 6
	s_add_i32 s44, s65, s59
	s_ashr_i32 s45, s44, 31
	s_lshl_b64 s[44:45], s[44:45], 11
	v_lshl_add_u64 v[48:49], v[182:183], 0, s[44:45]
	v_cndmask_b32_e64 v50, 0, 1, s[62:63]
	v_cmp_ne_u32_e64 s[44:45], 1, v50
	s_andn2_b64 vcc, exec, s[62:63]
	v_lshl_add_u64 v[192:193], v[48:49], 0, v[170:171]
	s_cbranch_vccnz .LBB0_524
	v_readlane_b32 s98, v251, 40
	v_readlane_b32 s99, v251, 41
	v_add_u32_e32 v236, s65, v200
	s_nop 1
	v_mov_b64_e32 v[238:239], s[98:99]
	v_mad_i64_i32 v[238:239], s[100:101], v236, s57, v[238:239]
	v_lshl_add_u64 v[238:239], v[238:239], 0, s[2:3]
	v_mov_b32_e32 v236, v180
	v_mov_b32_e32 v237, v165
	v_lshl_add_u64 v[238:239], v[238:239], 0, v[236:237]
	s_mov_b64 s[100:101], 0x1400
	v_lshl_add_u64 v[238:239], v[238:239], 0, s[100:101]
	global_load_dwordx4 v[228:231], v[238:239], off
	global_load_dwordx4 v[232:235], v[238:239], off offset:16
	v_add_co_u32_e32 v52, vcc, 0x1000, v192
	global_load_dword v48, v[192:193], off
	global_load_dword v49, v[192:193], off offset:2048
	v_addc_co_u32_e32 v53, vcc, 0, v193, vcc
	v_add_co_u32_e32 v54, vcc, 0x4000, v192
	global_load_dword v50, v[52:53], off
	global_load_dword v51, v[52:53], off offset:2048
	v_addc_co_u32_e32 v55, vcc, 0, v193, vcc
	v_add_co_u32_e32 v56, vcc, 0x5000, v192
	global_load_dword v52, v[54:55], off
	global_load_dword v53, v[54:55], off offset:2048
	v_addc_co_u32_e32 v57, vcc, 0, v193, vcc
	v_add_co_u32_e32 v58, vcc, 0x8000, v192
	global_load_dword v54, v[56:57], off
	global_load_dword v55, v[56:57], off offset:2048
	v_addc_co_u32_e32 v59, vcc, 0, v193, vcc
	v_add_co_u32_e32 v60, vcc, 0x9000, v192
	global_load_dword v56, v[58:59], off
	global_load_dword v57, v[58:59], off offset:2048
	v_addc_co_u32_e32 v61, vcc, 0, v193, vcc
	v_add_co_u32_e32 v62, vcc, 0xc000, v192
	global_load_dword v58, v[60:61], off
	global_load_dword v59, v[60:61], off offset:2048
	v_addc_co_u32_e32 v63, vcc, 0, v193, vcc
	v_add_co_u32_e32 v64, vcc, 0xd000, v192
	global_load_dword v60, v[62:63], off
	global_load_dword v61, v[62:63], off offset:2048
	v_addc_co_u32_e32 v65, vcc, 0, v193, vcc
	global_load_dword v62, v[64:65], off
	global_load_dword v63, v[64:65], off offset:2048
	s_bitcmp0_b32 s48, 0
	s_cselect_b64 s[66:67], -1, 0
	s_and_saveexec_b64 s[48:49], s[36:37]
	s_cbranch_execnz .LBB0_525
	s_branch .LBB0_526

; __device__ __forceinline__ unsigned cvt_pk_bf16(float lo, float hi) { unsigned r; asm volatile("v_cvt_pk_bf16_f32 %0, %1, %2" : "=v"(r) : "v"(lo), "v"(hi)); return r; }
; #define LAS __attribute__((address_space(3)))
; __device__ __forceinline__ int crow(int r, int hi) { return (r & 3) + 8 * (r >> 2) + 4 * hi; }
; __device__ __forceinline__ void passC(const Params& p, const bf16* Hb, const float* SEG, float* Z0, bf16* MIX, LAS unsigned char* lds, int bid, int G, int wave_u) {
;     ...
;                 for (int mbs = 0; mbs < 2; ++mbs)
; #pragma unroll
;                     for (int s2 = 0; s2 < 2; ++s2) {
;                         u32x4 ww;
;                         if (mbs == 0) { ww.x = cvt_pk_bf16(S0[8 * s2 + 0], S0[8 * s2 + 1]); ww.y = cvt_pk_bf16(S0[8 * s2 + 2], S0[8 * s2 + 3]); ww.z = cvt_pk_bf16(S0[8 * s2 + 4], S0[8 * s2 + 5]); ww.w = cvt_pk_bf16(S0[8 * s2 + 6], S0[8 * s2 + 7]); }
;                         else { ww.x = cvt_pk_bf16(S1[8 * s2 + 0], S1[8 * s2 + 1]); ww.y = cvt_pk_bf16(S1[8 * s2 + 2], S1[8 * s2 + 3]); ww.z = cvt_pk_bf16(S1[8 * s2 + 4], S1[8 * s2 + 5]); ww.w = cvt_pk_bf16(S1[8 * s2 + 6], S1[8 * s2 + 7]); }
;                         LAS unsigned char* qa = lds + L_QT + (32 * pb + r32) * QSTR + (32 * mbs + 16 * s2 + 4 * hh) * 2;
;                         const u32x2 alo = *(LAS u32x2*)qa, ahi = *(LAS u32x2*)(qa + 16);
;                         const u32x4 aw = (u32x4){alo.x, alo.y, ahi.x, ahi.y};
;                         Z = __builtin_amdgcn_mfma_f32_32x32x16_bf16(__builtin_bit_cast(bf16x8, aw), __builtin_bit_cast(bf16x8, ww), Z, 0, 0, 0);
;                     }
;                 state_update(S0, 0, db, LV, lds, hh, q4, pp4, g1);
;                 state_update(S1, 1, db, LV, lds, hh, q4, pp4, g1);
;                 if (dir == 0) {
; #pragma unroll
;                     for (int r = 0; r < 16; ++r) Zg[(size_t)crow(r, hh) * 512] = Z[r];
;                 } else {
;                     LAS float* Zl = (LAS float*)(lds + L_Z);
; #pragma unroll
;                     for (int r = 0; r < 16; ++r) Zl[(32 * pb + crow(r, hh)) * ZS + 32 * db + r32] = Z[r];
;                     __syncthreads();
;                     { const int pr = tid >> 3, dv0 = (tid & 7) * 16;
;                       float v[16]; float ss = 0.f;
; #pragma unroll
;                       for (int i = 0; i < 16; ++i) { v[i] = Zl[pr * ZS + dv0 + i]; ss += v[i] * v[i]; }
.LBB0_596:
	v_add_u32_e32 v68, v210, v212
	v_add_u32_e32 v72, 0x5800, v68
	v_cvt_pk_bf16_f32 v64, v16, v17
	v_cvt_pk_bf16_f32 v65, v18, v19
	v_cvt_pk_bf16_f32 v66, v20, v21
	v_cvt_pk_bf16_f32 v67, v22, v23
	ds_read2_b64 v[68:71], v72 offset0:64 offset1:66
	v_add_u32_e32 v128, 0, v209
	s_mov_b64 s[44:45], -1
	s_and_b64 vcc, exec, s[62:63]
	s_waitcnt vmcnt(0) lgkmcnt(0)
	v_mfma_f32_32x32x16_bf16 v[48:63], v[68:71], v[64:67], v[48:63]
	v_cvt_pk_bf16_f32 v64, v24, v25
	v_cvt_pk_bf16_f32 v65, v26, v27
	v_cvt_pk_bf16_f32 v66, v28, v29
	v_cvt_pk_bf16_f32 v67, v30, v31
	ds_read2_b64 v[68:71], v72 offset0:68 offset1:70
	s_waitcnt lgkmcnt(0)
	v_mfma_f32_32x32x16_bf16 v[48:63], v[68:71], v[64:67], v[48:63]
	v_cvt_pk_bf16_f32 v64, v32, v33
	v_cvt_pk_bf16_f32 v65, v34, v35
	v_cvt_pk_bf16_f32 v66, v36, v37
	v_cvt_pk_bf16_f32 v67, v38, v39
	ds_read2_b64 v[68:71], v72 offset0:72 offset1:74
	s_waitcnt lgkmcnt(0)
	v_mfma_f32_32x32x16_bf16 v[48:63], v[68:71], v[64:67], v[48:63]
	v_cvt_pk_bf16_f32 v64, v40, v41
	v_cvt_pk_bf16_f32 v65, v42, v43
	v_cvt_pk_bf16_f32 v66, v44, v45
	v_cvt_pk_bf16_f32 v67, v46, v47
	ds_read2_b64 v[68:71], v72 offset0:76 offset1:78
	s_waitcnt lgkmcnt(0)
	v_mfma_f32_32x32x16_bf16 v[48:63], v[68:71], v[64:67], v[48:63]
	v_add3_u32 v68, v213, s68, v214
	ds_read_b64_tr_b16 v[64:65], v220 offset:32256
	ds_read_b64_tr_b16 v[66:67], v220 offset:32832
	ds_read_b64_tr_b16 v[108:109], v68
	ds_read_b64_tr_b16 v[110:111], v68 offset:1280
	s_waitcnt lgkmcnt(0)
	v_mfma_f32_32x32x16_bf16 v[16:31], v[64:67], v[108:111], v[16:31]
	ds_read_b64_tr_b16 v[64:65], v220 offset:34560
	ds_read_b64_tr_b16 v[66:67], v220 offset:35136
	ds_read_b64_tr_b16 v[112:113], v68 offset:5120
	ds_read_b64_tr_b16 v[114:115], v68 offset:6400
	s_waitcnt lgkmcnt(0)
	v_mfma_f32_32x32x16_bf16 v[16:31], v[64:67], v[112:115], v[16:31]
	ds_read_b64_tr_b16 v[64:65], v220 offset:36864
	ds_read_b64_tr_b16 v[66:67], v220 offset:37440
	ds_read_b64_tr_b16 v[116:117], v68 offset:10240
	ds_read_b64_tr_b16 v[118:119], v68 offset:11520
	s_waitcnt lgkmcnt(0)
	v_mfma_f32_32x32x16_bf16 v[16:31], v[64:67], v[116:119], v[16:31]
	ds_read_b64_tr_b16 v[64:65], v220 offset:39168
	ds_read_b64_tr_b16 v[66:67], v220 offset:39744
	ds_read_b64_tr_b16 v[120:121], v68 offset:15360
	ds_read_b64_tr_b16 v[122:123], v68 offset:16640
	s_waitcnt lgkmcnt(0)
	v_mfma_f32_32x32x16_bf16 v[16:31], v[64:67], v[120:123], v[16:31]
	ds_read_b128 v[76:79], v128 offset:22528
	ds_read_b128 v[72:75], v128 offset:22560
	ds_read_b128 v[68:71], v128 offset:22592
	ds_read_b128 v[64:67], v128 offset:22624
	ds_read_b64_tr_b16 v[124:125], v220 offset:32320
	ds_read_b64_tr_b16 v[126:127], v220 offset:32896
	s_waitcnt lgkmcnt(0)
	v_mfma_f32_32x32x16_bf16 v[32:47], v[124:127], v[108:111], v[32:47]
	ds_read_b64_tr_b16 v[108:109], v220 offset:34624
	ds_read_b64_tr_b16 v[110:111], v220 offset:35200
	s_waitcnt lgkmcnt(0)
	v_mfma_f32_32x32x16_bf16 v[32:47], v[108:111], v[112:115], v[32:47]
	ds_read_b64_tr_b16 v[108:109], v220 offset:36928
	ds_read_b64_tr_b16 v[110:111], v220 offset:37504
	s_waitcnt lgkmcnt(0)
	v_mfma_f32_32x32x16_bf16 v[32:47], v[108:111], v[116:119], v[32:47]
	ds_read_b64_tr_b16 v[108:109], v220 offset:39232
	ds_read_b64_tr_b16 v[110:111], v220 offset:39808
	s_waitcnt lgkmcnt(0)
	v_mfma_f32_32x32x16_bf16 v[32:47], v[108:111], v[120:123], v[32:47]
	ds_read_b128 v[120:123], v128 offset:22656
	ds_read_b128 v[116:119], v128 offset:22688
	ds_read_b128 v[112:115], v128 offset:22720
	ds_read_b128 v[108:111], v128 offset:22752
	s_cbranch_vccz .LBB0_598
	v_add_u32_e32 v124, 0x400, v221
	ds_write2_b32 v124, v50, v51 offset0:8 offset1:140
	v_add_u32_e32 v124, 0x1000, v221
	ds_write2_b32 v124, v52, v53 offset0:32 offset1:164
	v_add_u32_e32 v124, 0x1400, v221
	ds_write2_b32 v124, v54, v55 offset0:40 offset1:172
	v_add_u32_e32 v124, 0x2000, v221
	ds_write2_b32 v124, v56, v57 offset0:64 offset1:196
	v_add_u32_e32 v124, 0x2400, v221
	ds_write2_b32 v124, v58, v59 offset0:72 offset1:204
	v_add_u32_e32 v124, 0x3000, v221
	ds_write2_b32 v124, v60, v61 offset0:96 offset1:228
	v_add_u32_e32 v124, 0x3400, v221
	ds_write2_b32 v221, v48, v49 offset1:132
	ds_write2_b32 v124, v62, v63 offset0:104 offset1:236
	s_waitcnt lgkmcnt(0)
	s_barrier
	global_load_dwordx4 v[156:159], v[238:239], off
	global_load_dwordx4 v[140:143], v[238:239], off offset:16
	global_load_dwordx4 v[144:147], v[174:175], off offset:32
	global_load_dwordx4 v[152:155], v[174:175], off offset:16
	global_load_dwordx4 v[160:163], v[174:175], off
	ds_read_b128 v[148:151], v215
	ds_read_b128 v[132:135], v215 offset:16
	ds_read_b128 v[128:131], v215 offset:32
	ds_read_b128 v[124:127], v215 offset:48
	v_readlane_b32 s44, v251, 40
	s_waitcnt lgkmcnt(3)
	v_mul_f32_e32 v138, v149, v149
	v_fmac_f32_e32 v138, v148, v148
	v_fmac_f32_e32 v138, v150, v150
	v_fmac_f32_e32 v138, v151, v151
	s_waitcnt lgkmcnt(2)
	v_fmac_f32_e32 v138, v132, v132
	v_fmac_f32_e32 v138, v133, v133
	v_fmac_f32_e32 v138, v134, v134
	v_fmac_f32_e32 v138, v135, v135
	s_waitcnt lgkmcnt(1)
	v_fmac_f32_e32 v138, v128, v128
	v_fmac_f32_e32 v138, v129, v129
	v_fmac_f32_e32 v138, v130, v130
	v_fmac_f32_e32 v138, v131, v131
	s_waitcnt lgkmcnt(0)
	v_pk_mul_f32 v[136:137], v[124:125], v[124:125]
	v_readlane_b32 s45, v251, 41
	v_add_f32_e32 v136, v138, v136
	v_add_f32_e32 v138, v136, v137
	v_pk_mul_f32 v[136:137], v[126:127], v[126:127]
	v_add_u32_e32 v194, s65, v200
	v_add_f32_e32 v136, v138, v136
	v_and_b32_e32 v138, 64, v224
	v_add_f32_e32 v136, v136, v137
	v_xor_b32_e32 v137, 1, v224
	v_add_u32_e32 v138, 64, v138
	v_cmp_lt_i32_e32 vcc, v137, v138
	v_mov_b32_e32 v181, v165
	v_ashrrev_i32_e32 v195, 31, v194
	v_cndmask_b32_e32 v137, v224, v137, vcc
	v_lshlrev_b32_e32 v137, 2, v137
	ds_bpermute_b32 v137, v137, v136
	s_waitcnt lgkmcnt(0)
; __device__ __forceinline__ unsigned cvt_pk_bf16(float lo, float hi) { unsigned r; asm volatile("v_cvt_pk_bf16_f32 %0, %1, %2" : "=v"(r) : "v"(lo), "v"(hi)); return r; }
; __device__ __forceinline__ float bf2f(unsigned h) { return __uint_as_float(h << 16); }
; __device__ __forceinline__ float fexp(float x) { return __builtin_amdgcn_exp2f(x * LOG2E); }
; __device__ __forceinline__ void passC(const Params& p, const bf16* Hb, const float* SEG, float* Z0, bf16* MIX, LAS unsigned char* lds, int bid, int G, int wave_u) {
;     ...
;                       ss += __shfl_xor(ss, 1); ss += __shfl_xor(ss, 2); ss += __shfl_xor(ss, 4);
;                       const float rn = __builtin_amdgcn_rsqf(ss * (1.f / 128.f) + 1e-5f);
;                       const bf16* grp_ = Hb + (size_t)(rowbase + pr) * LDH + O_GR + head * 128 + dv0;
;                       const u32x4 g0 = *(const u32x4*)grp_, g1v = *(const u32x4*)(grp_ + 8);
;                       const float* gn = p.in[13] + dv0;
;                       float o[16];
; #pragma unroll
;                       for (int i = 0; i < 16; ++i) { const unsigned wv = (i < 8) ? g0[i >> 1] : g1v[(i - 8) >> 1]; const float gr = bf2f((i & 1) ? (wv >> 16) : (wv & 0xffffu));
;                           const float sl = gr * __builtin_amdgcn_rcpf(1.f + fexp(-gr)); o[i] = v[i] * rn * gn[i] * sl; }
;                       u32x4 a, b; a.x = cvt_pk_bf16(o[0], o[1]); a.y = cvt_pk_bf16(o[2], o[3]); a.z = cvt_pk_bf16(o[4], o[5]); a.w = cvt_pk_bf16(o[6], o[7]);
;                       b.x = cvt_pk_bf16(o[8], o[9]); b.y = cvt_pk_bf16(o[10], o[11]); b.z = cvt_pk_bf16(o[12], o[13]); b.w = cvt_pk_bf16(o[14], o[15]);
;                       bf16* orow = MIX + (size_t)(rowbase + pr) * D + 512 + head * 128 + dv0;
;                       __builtin_nontemporal_store(a, (u32x4*)orow); __builtin_nontemporal_store(b, (u32x4*)(orow + 8)); }
	v_add_f32_e32 v136, v136, v137
	v_xor_b32_e32 v137, 2, v224
	v_cmp_lt_i32_e32 vcc, v137, v138
	s_nop 1
	v_cndmask_b32_e32 v137, v224, v137, vcc
	v_lshlrev_b32_e32 v137, 2, v137
	ds_bpermute_b32 v137, v137, v136
	s_waitcnt lgkmcnt(0)
	v_add_f32_e32 v136, v136, v137
	v_xor_b32_e32 v137, 4, v224
	v_cmp_lt_i32_e32 vcc, v137, v138
	s_nop 1
	v_cndmask_b32_e32 v137, v224, v137, vcc
	v_lshlrev_b32_e32 v137, 2, v137
	ds_bpermute_b32 v137, v137, v136
	s_waitcnt lgkmcnt(0)
	v_add_f32_e32 v136, v136, v137
	v_fmamk_f32 v136, v136, 0x3c000000, v222
	v_rsq_f32_e32 v189, v136
	global_load_dwordx4 v[136:139], v[174:175], off offset:48
	s_nop 0
	v_mul_f32_e32 v196, v148, v189
	v_mul_f32_e32 v129, v129, v189
	v_mul_f32_e32 v125, v125, v189
	s_mov_b64 s[44:45], 0
	s_waitcnt vmcnt(4)
	v_lshlrev_b32_e32 v197, 16, v156
	v_mul_f32_e32 v236, 0xbfb8aa3b, v197
	v_exp_f32_e32 v236, v236
	s_nop 0
	v_add_f32_e32 v236, 1.0, v236
	v_rcp_f32_e32 v227, v236
	s_waitcnt vmcnt(0)
	v_mov_b32_e32 v226, v160
	v_pk_mul_f32 v[196:197], v[226:227], v[196:197]
	v_mov_b32_e32 v226, v161
	v_mul_f32_e32 v148, v196, v197
	v_and_b32_e32 v197, 0xffff0000, v156
	v_mul_f32_e32 v156, 0xbfb8aa3b, v197
	v_exp_f32_e32 v156, v156
	v_mul_f32_e32 v196, v149, v189
	v_add_f32_e32 v156, 1.0, v156
	v_rcp_f32_e32 v227, v156
	s_nop 0
	v_pk_mul_f32 v[160:161], v[226:227], v[196:197]
	s_nop 0
	v_mul_f32_e32 v149, v160, v161
	v_lshlrev_b32_e32 v161, 16, v157
	v_mul_f32_e32 v156, 0xbfb8aa3b, v161
	v_exp_f32_e32 v156, v156
	v_and_b32_e32 v157, 0xffff0000, v157
	v_mul_f32_e32 v160, v150, v189
	v_mul_f32_e32 v150, 0xbfb8aa3b, v157
	v_add_f32_e32 v156, 1.0, v156
	v_rcp_f32_e32 v197, v156
	v_exp_f32_e32 v150, v150
	v_mov_b32_e32 v196, v162
	v_mov_b32_e32 v156, v163
	v_pk_mul_f32 v[160:161], v[196:197], v[160:161]
	v_add_f32_e32 v150, 1.0, v150
	v_mul_f32_e32 v162, v160, v161
	v_rcp_f32_e32 v161, v150
	v_mul_f32_e32 v160, v151, v189
	v_pk_mul_f32 v[150:151], v[160:161], v[156:157]
	s_nop 0
	v_mul_f32_e32 v160, v150, v151
	v_lshlrev_b32_e32 v151, 16, v158
	v_mul_f32_e32 v150, 0xbfb8aa3b, v151
	v_exp_f32_e32 v150, v150
	v_mul_f32_e32 v156, v132, v189
	v_add_f32_e32 v150, 1.0, v150
	v_rcp_f32_e32 v157, v150
	v_mov_b32_e32 v150, v152
	v_pk_mul_f32 v[150:151], v[156:157], v[150:151]
	s_nop 0
	v_mul_f32_e32 v152, v150, v151
	v_and_b32_e32 v151, 0xffff0000, v158
	v_mul_f32_e32 v132, 0xbfb8aa3b, v151
	v_exp_f32_e32 v132, v132
	v_mul_f32_e32 v156, v133, v189
	v_mov_b32_e32 v150, v153
	v_add_f32_e32 v132, 1.0, v132
	v_rcp_f32_e32 v157, v132
	s_nop 0
	v_pk_mul_f32 v[132:133], v[156:157], v[150:151]
	s_nop 0
	v_mul_f32_e32 v153, v132, v133
	v_lshlrev_b32_e32 v132, 16, v159
	v_mul_f32_e32 v133, 0xbfb8aa3b, v132
	v_exp_f32_e32 v133, v133
	v_mul_f32_e32 v151, v134, v189
	v_add_f32_e32 v133, 1.0, v133
	v_rcp_f32_e32 v150, v133
	v_mov_b32_e32 v133, v154
	v_and_b32_e32 v154, 0xffff0000, v159
	v_pk_mul_f32 v[132:133], v[150:151], v[132:133]
	s_nop 0
	v_mul_f32_e32 v150, v132, v133
	v_mul_f32_e32 v132, 0xbfb8aa3b, v154
	v_exp_f32_e32 v132, v132
	v_mul_f32_e32 v133, v135, v189
	v_mul_f32_e32 v135, v128, v189
	v_add_f32_e32 v132, 1.0, v132
	v_rcp_f32_e32 v132, v132
	s_nop 0
	v_pk_mul_f32 v[132:133], v[132:133], v[154:155]
	s_nop 0
	v_mul_f32_e32 v151, v132, v133
	v_lshlrev_b32_e32 v132, 16, v140
	v_mul_f32_e32 v133, 0xbfb8aa3b, v132
	v_exp_f32_e32 v133, v133
	s_nop 0
	v_add_f32_e32 v133, 1.0, v133
	v_rcp_f32_e32 v134, v133
	v_mov_b32_e32 v133, v144
	v_and_b32_e32 v144, 0xffff0000, v140
	v_mul_f32_e32 v128, 0xbfb8aa3b, v144
	v_exp_f32_e32 v128, v128
	v_pk_mul_f32 v[132:133], v[134:135], v[132:133]
	v_add_f32_e32 v128, 1.0, v128
	v_rcp_f32_e32 v128, v128
	v_mul_f32_e32 v134, v132, v133
	v_mul_f32_e32 v133, v130, v189
	v_pk_mul_f32 v[128:129], v[128:129], v[144:145]
	s_nop 0
	v_mul_f32_e32 v135, v128, v129
	v_lshlrev_b32_e32 v128, 16, v141
	v_mul_f32_e32 v129, 0xbfb8aa3b, v128
	v_exp_f32_e32 v129, v129
	s_nop 0
	v_add_f32_e32 v129, 1.0, v129
	v_rcp_f32_e32 v132, v129
	v_mov_b32_e32 v129, v146
	v_and_b32_e32 v146, 0xffff0000, v141
	v_pk_mul_f32 v[128:129], v[132:133], v[128:129]
	s_nop 0
	v_mul_f32_e32 v132, v128, v129
	v_mul_f32_e32 v128, 0xbfb8aa3b, v146
	v_exp_f32_e32 v128, v128
	v_mul_f32_e32 v129, v131, v189
	v_mul_f32_e32 v131, v124, v189
	v_add_f32_e32 v128, 1.0, v128
	v_rcp_f32_e32 v128, v128
	s_nop 0
	v_pk_mul_f32 v[128:129], v[128:129], v[146:147]
	s_nop 0
	v_mul_f32_e32 v133, v128, v129
	v_lshlrev_b32_e32 v128, 16, v142
	v_mul_f32_e32 v129, 0xbfb8aa3b, v128
	v_exp_f32_e32 v129, v129
	s_nop 0
	v_add_f32_e32 v129, 1.0, v129
	v_rcp_f32_e32 v130, v129
	v_mov_b32_e32 v129, v136
	v_and_b32_e32 v136, 0xffff0000, v142
	v_mul_f32_e32 v124, 0xbfb8aa3b, v136
	v_exp_f32_e32 v124, v124
	v_pk_mul_f32 v[128:129], v[130:131], v[128:129]
	v_add_f32_e32 v124, 1.0, v124
	v_rcp_f32_e32 v124, v124
	v_mul_f32_e32 v130, v128, v129
	v_mul_f32_e32 v129, v126, v189
	v_pk_mul_f32 v[124:125], v[124:125], v[136:137]
	s_nop 0
	v_mul_f32_e32 v131, v124, v125
	v_lshlrev_b32_e32 v124, 16, v143
	v_mul_f32_e32 v125, 0xbfb8aa3b, v124
	v_exp_f32_e32 v125, v125
	s_nop 0
	v_add_f32_e32 v125, 1.0, v125
	v_rcp_f32_e32 v128, v125
	v_mov_b32_e32 v125, v138
	v_and_b32_e32 v138, 0xffff0000, v143
	v_pk_mul_f32 v[124:125], v[128:129], v[124:125]
	s_nop 0
	v_mul_f32_e32 v136, v124, v125
	v_mul_f32_e32 v124, 0xbfb8aa3b, v138
	v_exp_f32_e32 v124, v124
	v_mul_f32_e32 v125, v127, v189
	v_add_f32_e32 v124, 1.0, v124
	v_rcp_f32_e32 v124, v124
	s_nop 0
	v_pk_mul_f32 v[124:125], v[124:125], v[138:139]
	s_nop 0
	v_mul_f32_e32 v137, v124, v125
	v_cvt_pk_bf16_f32 v124, v148, v149
	v_cvt_pk_bf16_f32 v125, v162, v160
	v_cvt_pk_bf16_f32 v126, v152, v153
	v_cvt_pk_bf16_f32 v127, v150, v151
	v_cvt_pk_bf16_f32 v128, v134, v135
	v_cvt_pk_bf16_f32 v129, v132, v133
	v_lshlrev_b64 v[132:133], 11, v[194:195]
	v_lshl_add_u64 v[132:133], v[186:187], 0, v[132:133]
	v_cvt_pk_bf16_f32 v130, v130, v131
	v_cvt_pk_bf16_f32 v131, v136, v137
	global_store_dwordx4 v[132:133], v[124:127], off offset:1024 nt
	global_store_dwordx4 v[132:133], v[128:131], off offset:1040 nt
